# radix-select histogram scan: 16 dependent LDS round trips batched into two read groups, bit-mask select
# baseline (speedup 1.0000x reference)
; #define LAS __attribute__((address_space(3)))
; __device__ __forceinline__ void scan_hist(LAS char* lds, int shiftbits) {
;     LAS unsigned* hist = (LAS unsigned*)(lds + L_HIST); LAS unsigned* part = (LAS unsigned*)(lds + L_PART);
;     LAS unsigned* pref = (LAS unsigned*)(lds + L_PREF); LAS unsigned* kremS = (LAS unsigned*)(lds + L_KREM); LAS unsigned* neqS = (LAS unsigned*)(lds + L_NEQ);
;     const int tid = opaque_tid(), q = tid & 15, g = tid >> 4;
;     unsigned hv[8]; unsigned s = 0;
; #pragma unroll
;     for (int j = 0; j < 8; ++j) { hv[j] = hist[(8 * g + j) * 16 + q]; s += hv[j]; }
;     const unsigned krem = kremS[q];
;     part[g * 16 + q] = s;
;     __syncthreads();
;     unsigned above = 0;
; #pragma unroll
;     for (int gg = 0; gg < 32; ++gg) { const unsigned pv = part[gg * 16 + q]; above += (gg > g) ? pv : 0u; }
;     if (above < krem && krem <= above + s) {
;         unsigned cum = above; int bsel = 8 * g; unsigned hsel = 0; bool done = false;
; #pragma unroll
;         for (int j = 7; j >= 0; --j) { if (!done) { if (cum + hv[j] >= krem) { bsel = 8 * g + j; hsel = hv[j]; done = true; } else cum += hv[j]; } }
;         pref[q] = (pref[q] << shiftbits) | (unsigned)bsel; kremS[q] = krem - cum; neqS[q] = hsel;
;     }
.LBB0_672:
	s_waitcnt lgkmcnt(0)
	s_barrier
	s_getreg_b32 s2, hwreg(HW_REG_HW_ID, 0, 6)
	s_lshl_b32 s2, s2, 2
	s_and_b32 s2, s2, 0xfc
	s_add_i32 s2, s2, 0x20040
	v_mov_b32_e32 v2, s2
	ds_read_b32 v2, v2
	s_waitcnt lgkmcnt(0)
	v_readfirstlane_b32 s2, v2
	v_mov_b32_e32 v2, v1
	s_nop 0
	v_mbcnt_lo_u32_b32 v2, -1, v2
	v_mbcnt_hi_u32_b32 v2, -1, v2
	v_lshl_or_b32 v21, s2, 6, v2
	v_and_b32_e32 v2, 15, v2
	v_ashrrev_i32_e32 v20, 4, v21
	v_lshl_add_u32 v18, v2, 2, 0
	v_lshl_add_u32 v2, v20, 9, v18
	v_add_u32_e32 v4, 0x4000, v2
	ds_read2_b32 v[2:3], v4 offset1:16
	ds_read2_b32 v[6:7], v4 offset0:32 offset1:48
	ds_read2_b32 v[8:9], v4 offset0:64 offset1:80
	v_lshl_add_u32 v22, v21, 2, 0
	v_add_u32_e32 v25, 0x8000, v18
	s_waitcnt lgkmcnt(2)
	v_add_u32_e32 v5, v3, v2
	s_waitcnt lgkmcnt(1)
	v_add3_u32 v5, v5, v6, v7
	s_waitcnt lgkmcnt(0)
	v_add3_u32 v19, v5, v8, v9
	ds_read2_b32 v[4:5], v4 offset0:96 offset1:112
	v_ashrrev_i32_e32 v21, 31, v21
	v_cmp_gt_i32_e32 vcc, 1, v20
	s_waitcnt lgkmcnt(0)
	v_add3_u32 v24, v19, v4, v5
	ds_read_b32 v19, v18 offset:34944
	ds_write_b32 v22, v24 offset:32832
	s_waitcnt lgkmcnt(0)
	s_barrier
	v_mov_b32_e32 v152, -2
	v_lshlrev_b32_e32 v152, v20, v152
	v_add_u32_e32 v153, 0x8200, v18
	v_add_u32_e32 v154, 0x8400, v18
	v_add_u32_e32 v155, 0x8600, v18
	ds_read2_b32 v[26:27], v25 offset0:16 offset1:32
	ds_read2_b32 v[28:29], v25 offset0:48 offset1:64
	ds_read2_b32 v[30:31], v25 offset0:80 offset1:96
	ds_read2_b32 v[32:33], v25 offset0:112 offset1:128
	ds_read2_b32 v[34:35], v25 offset0:144 offset1:160
	ds_read2_b32 v[36:37], v25 offset0:176 offset1:192
	ds_read2_b32 v[38:39], v25 offset0:208 offset1:224
	ds_read2_b32 v[40:41], v153 offset0:112 offset1:128
	s_waitcnt lgkmcnt(4)
	ds_read2_b32 v[42:43], v154 offset0:16 offset1:32
	ds_read2_b32 v[44:45], v154 offset0:48 offset1:64
	ds_read2_b32 v[46:47], v154 offset0:80 offset1:96
	ds_read2_b32 v[48:49], v154 offset0:112 offset1:128
	ds_read2_b32 v[50:51], v154 offset0:144 offset1:160
	ds_read2_b32 v[52:53], v154 offset0:176 offset1:192
	ds_read2_b32 v[156:157], v154 offset0:208 offset1:224
	ds_read2_b32 v[158:159], v155 offset0:112 offset1:128
	v_mov_b32_e32 v22, 0
	v_mov_b32_e32 v23, 0
	s_waitcnt lgkmcnt(8)
	v_bfe_u32 v150, v152, 0, 1
	v_mad_u32_u24 v22, v150, v26, v22
	v_bfe_u32 v151, v152, 1, 1
	v_mad_u32_u24 v23, v151, v27, v23
	v_bfe_u32 v150, v152, 2, 1
	v_mad_u32_u24 v22, v150, v28, v22
	v_bfe_u32 v151, v152, 3, 1
	v_mad_u32_u24 v23, v151, v29, v23
	v_bfe_u32 v150, v152, 4, 1
	v_mad_u32_u24 v22, v150, v30, v22
	v_bfe_u32 v151, v152, 5, 1
	v_mad_u32_u24 v23, v151, v31, v23
	v_bfe_u32 v150, v152, 6, 1
	v_mad_u32_u24 v22, v150, v32, v22
	v_bfe_u32 v151, v152, 7, 1
	v_mad_u32_u24 v23, v151, v33, v23
	v_bfe_u32 v150, v152, 8, 1
	v_mad_u32_u24 v22, v150, v34, v22
	v_bfe_u32 v151, v152, 9, 1
	v_mad_u32_u24 v23, v151, v35, v23
	v_bfe_u32 v150, v152, 10, 1
	v_mad_u32_u24 v22, v150, v36, v22
	v_bfe_u32 v151, v152, 11, 1
	v_mad_u32_u24 v23, v151, v37, v23
	v_bfe_u32 v150, v152, 12, 1
	v_mad_u32_u24 v22, v150, v38, v22
	v_bfe_u32 v151, v152, 13, 1
	v_mad_u32_u24 v23, v151, v39, v23
	v_bfe_u32 v150, v152, 14, 1
	v_mad_u32_u24 v22, v150, v40, v22
	v_bfe_u32 v151, v152, 15, 1
	v_mad_u32_u24 v23, v151, v41, v23
	s_waitcnt lgkmcnt(0)
	v_bfe_u32 v150, v152, 16, 1
	v_mad_u32_u24 v22, v150, v42, v22
	v_bfe_u32 v151, v152, 17, 1
	v_mad_u32_u24 v23, v151, v43, v23
	v_bfe_u32 v150, v152, 18, 1
	v_mad_u32_u24 v22, v150, v44, v22
	v_bfe_u32 v151, v152, 19, 1
	v_mad_u32_u24 v23, v151, v45, v23
	v_bfe_u32 v150, v152, 20, 1
	v_mad_u32_u24 v22, v150, v46, v22
	v_bfe_u32 v151, v152, 21, 1
	v_mad_u32_u24 v23, v151, v47, v23
	v_bfe_u32 v150, v152, 22, 1
	v_mad_u32_u24 v22, v150, v48, v22
	v_bfe_u32 v151, v152, 23, 1
	v_mad_u32_u24 v23, v151, v49, v23
	v_bfe_u32 v150, v152, 24, 1
	v_mad_u32_u24 v22, v150, v50, v22
	v_bfe_u32 v151, v152, 25, 1
	v_mad_u32_u24 v23, v151, v51, v23
	v_bfe_u32 v150, v152, 26, 1
	v_mad_u32_u24 v22, v150, v52, v22
	v_bfe_u32 v151, v152, 27, 1
	v_mad_u32_u24 v23, v151, v53, v23
	v_bfe_u32 v150, v152, 28, 1
	v_mad_u32_u24 v22, v150, v156, v22
	v_bfe_u32 v151, v152, 29, 1
	v_mad_u32_u24 v23, v151, v157, v23
	v_bfe_u32 v150, v152, 30, 1
	v_mad_u32_u24 v22, v150, v158, v22
	v_bfe_u32 v151, v152, 31, 1
	v_mad_u32_u24 v23, v151, v159, v23
	v_add_u32_e32 v22, v22, v23
	v_add_u32_e32 v21, v22, v24
	v_cmp_lt_u32_e32 vcc, v22, v19
	v_cmp_le_u32_e64 s[2:3], v19, v21
	s_and_b64 s[2:3], vcc, s[2:3]
	s_and_saveexec_b64 s[4:5], s[2:3]
	s_xor_b64 s[2:3], exec, s[4:5]
	s_cbranch_execz .LBB0_702
	v_lshlrev_b32_e32 v20, 3, v20
	v_add_u32_e32 v23, v22, v5
	v_cmp_lt_u32_e32 vcc, v23, v19
	v_or_b32_e32 v21, 7, v20
	s_mov_b64 s[4:5], -1
	s_mov_b64 s[8:9], -1
	s_and_saveexec_b64 s[6:7], vcc
	s_cbranch_execz .LBB0_677
	v_add_u32_e32 v22, v23, v4
	v_cmp_ge_u32_e32 vcc, v22, v19
	v_mov_b32_e32 v5, 0
	s_mov_b64 s[8:9], 0
	v_mov_b32_e32 v21, v20
	s_and_saveexec_b64 s[10:11], vcc
	s_mov_b64 s[8:9], exec
	v_or_b32_e32 v21, 6, v20
	v_mov_b32_e32 v5, v4
	v_mov_b32_e32 v22, v23
	s_or_b64 exec, exec, s[10:11]
	s_orn2_b64 s[8:9], s[8:9], exec

; #define LAS __attribute__((address_space(3)))
; __device__ __forceinline__ void scan_hist(LAS char* lds, int shiftbits) {
;     LAS unsigned* hist = (LAS unsigned*)(lds + L_HIST); LAS unsigned* part = (LAS unsigned*)(lds + L_PART);
;     LAS unsigned* pref = (LAS unsigned*)(lds + L_PREF); LAS unsigned* kremS = (LAS unsigned*)(lds + L_KREM); LAS unsigned* neqS = (LAS unsigned*)(lds + L_NEQ);
;     const int tid = opaque_tid(), q = tid & 15, g = tid >> 4;
;     unsigned hv[8]; unsigned s = 0;
; #pragma unroll
;     for (int j = 0; j < 8; ++j) { hv[j] = hist[(8 * g + j) * 16 + q]; s += hv[j]; }
;     const unsigned krem = kremS[q];
;     part[g * 16 + q] = s;
;     __syncthreads();
;     unsigned above = 0;
; #pragma unroll
;     for (int gg = 0; gg < 32; ++gg) { const unsigned pv = part[gg * 16 + q]; above += (gg > g) ? pv : 0u; }
;     if (above < krem && krem <= above + s) {
;         unsigned cum = above; int bsel = 8 * g; unsigned hsel = 0; bool done = false;
; #pragma unroll
;         for (int j = 7; j >= 0; --j) { if (!done) { if (cum + hv[j] >= krem) { bsel = 8 * g + j; hsel = hv[j]; done = true; } else cum += hv[j]; } }
;         pref[q] = (pref[q] << shiftbits) | (unsigned)bsel; kremS[q] = krem - cum; neqS[q] = hsel;
;     }
.LBB0_719:
	s_waitcnt lgkmcnt(0)
	s_barrier
	s_getreg_b32 s16, hwreg(HW_REG_HW_ID, 0, 6)
	s_lshl_b32 s16, s16, 2
	s_and_b32 s16, s16, 0xfc
	s_add_i32 s16, s16, 0x20040
	v_mov_b32_e32 v2, s16
	ds_read_b32 v2, v2
	s_waitcnt lgkmcnt(0)
	v_readfirstlane_b32 s16, v2
	v_mov_b32_e32 v2, 0
	s_nop 0
	v_mbcnt_lo_u32_b32 v2, -1, v2
	v_mbcnt_hi_u32_b32 v2, -1, v2
	v_lshl_or_b32 v21, s16, 6, v2
	v_and_b32_e32 v2, 15, v2
	v_ashrrev_i32_e32 v20, 4, v21
	v_lshl_add_u32 v18, v2, 2, 0
	v_lshl_add_u32 v2, v20, 9, v18
	v_add_u32_e32 v4, 0x4000, v2
	ds_read2_b32 v[2:3], v4 offset1:16
	ds_read2_b32 v[6:7], v4 offset0:32 offset1:48
	ds_read2_b32 v[8:9], v4 offset0:64 offset1:80
	v_lshl_add_u32 v22, v21, 2, 0
	v_add_u32_e32 v25, 0x8000, v18
	s_waitcnt lgkmcnt(2)
	v_add_u32_e32 v5, v3, v2
	s_waitcnt lgkmcnt(1)
	v_add3_u32 v5, v5, v6, v7
	s_waitcnt lgkmcnt(0)
	v_add3_u32 v19, v5, v8, v9
	ds_read2_b32 v[4:5], v4 offset0:96 offset1:112
	v_ashrrev_i32_e32 v21, 31, v21
	v_cmp_gt_i32_e32 vcc, 1, v20
	s_waitcnt lgkmcnt(0)
	v_add3_u32 v24, v19, v4, v5
	ds_read_b32 v19, v18 offset:34944
	ds_write_b32 v22, v24 offset:32832
	s_waitcnt lgkmcnt(0)
	s_barrier
	v_mov_b32_e32 v152, -2
	v_lshlrev_b32_e32 v152, v20, v152
	v_add_u32_e32 v153, 0x8200, v18
	v_add_u32_e32 v154, 0x8400, v18
	v_add_u32_e32 v155, 0x8600, v18
	ds_read2_b32 v[26:27], v25 offset0:16 offset1:32
	ds_read2_b32 v[28:29], v25 offset0:48 offset1:64
	ds_read2_b32 v[30:31], v25 offset0:80 offset1:96
	ds_read2_b32 v[32:33], v25 offset0:112 offset1:128
	ds_read2_b32 v[34:35], v25 offset0:144 offset1:160
	ds_read2_b32 v[36:37], v25 offset0:176 offset1:192
	ds_read2_b32 v[38:39], v25 offset0:208 offset1:224
	ds_read2_b32 v[40:41], v153 offset0:112 offset1:128
	s_waitcnt lgkmcnt(4)
	ds_read2_b32 v[42:43], v154 offset0:16 offset1:32
	ds_read2_b32 v[44:45], v154 offset0:48 offset1:64
	ds_read2_b32 v[46:47], v154 offset0:80 offset1:96
	ds_read2_b32 v[48:49], v154 offset0:112 offset1:128
	ds_read2_b32 v[50:51], v154 offset0:144 offset1:160
	ds_read2_b32 v[52:53], v154 offset0:176 offset1:192
	ds_read2_b32 v[156:157], v154 offset0:208 offset1:224
	ds_read2_b32 v[158:159], v155 offset0:112 offset1:128
	v_mov_b32_e32 v22, 0
	v_mov_b32_e32 v23, 0
	s_waitcnt lgkmcnt(8)
	v_bfe_u32 v150, v152, 0, 1
	v_mad_u32_u24 v22, v150, v26, v22
	v_bfe_u32 v151, v152, 1, 1
	v_mad_u32_u24 v23, v151, v27, v23
	v_bfe_u32 v150, v152, 2, 1
	v_mad_u32_u24 v22, v150, v28, v22
	v_bfe_u32 v151, v152, 3, 1
	v_mad_u32_u24 v23, v151, v29, v23
	v_bfe_u32 v150, v152, 4, 1
	v_mad_u32_u24 v22, v150, v30, v22
	v_bfe_u32 v151, v152, 5, 1
	v_mad_u32_u24 v23, v151, v31, v23
	v_bfe_u32 v150, v152, 6, 1
	v_mad_u32_u24 v22, v150, v32, v22
	v_bfe_u32 v151, v152, 7, 1
	v_mad_u32_u24 v23, v151, v33, v23
	v_bfe_u32 v150, v152, 8, 1
	v_mad_u32_u24 v22, v150, v34, v22
	v_bfe_u32 v151, v152, 9, 1
	v_mad_u32_u24 v23, v151, v35, v23
	v_bfe_u32 v150, v152, 10, 1
	v_mad_u32_u24 v22, v150, v36, v22
	v_bfe_u32 v151, v152, 11, 1
	v_mad_u32_u24 v23, v151, v37, v23
	v_bfe_u32 v150, v152, 12, 1
	v_mad_u32_u24 v22, v150, v38, v22
	v_bfe_u32 v151, v152, 13, 1
	v_mad_u32_u24 v23, v151, v39, v23
	v_bfe_u32 v150, v152, 14, 1
	v_mad_u32_u24 v22, v150, v40, v22
	v_bfe_u32 v151, v152, 15, 1
	v_mad_u32_u24 v23, v151, v41, v23
	s_waitcnt lgkmcnt(0)
	v_bfe_u32 v150, v152, 16, 1
	v_mad_u32_u24 v22, v150, v42, v22
	v_bfe_u32 v151, v152, 17, 1
	v_mad_u32_u24 v23, v151, v43, v23
	v_bfe_u32 v150, v152, 18, 1
	v_mad_u32_u24 v22, v150, v44, v22
	v_bfe_u32 v151, v152, 19, 1
	v_mad_u32_u24 v23, v151, v45, v23
	v_bfe_u32 v150, v152, 20, 1
	v_mad_u32_u24 v22, v150, v46, v22
	v_bfe_u32 v151, v152, 21, 1
	v_mad_u32_u24 v23, v151, v47, v23
	v_bfe_u32 v150, v152, 22, 1
	v_mad_u32_u24 v22, v150, v48, v22
	v_bfe_u32 v151, v152, 23, 1
	v_mad_u32_u24 v23, v151, v49, v23
	v_bfe_u32 v150, v152, 24, 1
	v_mad_u32_u24 v22, v150, v50, v22
	v_bfe_u32 v151, v152, 25, 1
	v_mad_u32_u24 v23, v151, v51, v23
	v_bfe_u32 v150, v152, 26, 1
	v_mad_u32_u24 v22, v150, v52, v22
	v_bfe_u32 v151, v152, 27, 1
	v_mad_u32_u24 v23, v151, v53, v23
	v_bfe_u32 v150, v152, 28, 1
	v_mad_u32_u24 v22, v150, v156, v22
	v_bfe_u32 v151, v152, 29, 1
	v_mad_u32_u24 v23, v151, v157, v23
	v_bfe_u32 v150, v152, 30, 1
	v_mad_u32_u24 v22, v150, v158, v22
	v_bfe_u32 v151, v152, 31, 1
	v_mad_u32_u24 v23, v151, v159, v23
	v_add_u32_e32 v22, v22, v23
	v_add_u32_e32 v21, v22, v24
	v_cmp_lt_u32_e32 vcc, v22, v19
	v_cmp_le_u32_e64 s[16:17], v19, v21
	s_and_b64 s[16:17], vcc, s[16:17]
	s_and_saveexec_b64 s[28:29], s[16:17]
	s_xor_b64 s[16:17], exec, s[28:29]
	s_cbranch_execz .LBB0_705
	v_lshlrev_b32_e32 v20, 3, v20
	v_add_u32_e32 v23, v22, v5
	v_cmp_lt_u32_e32 vcc, v23, v19
	v_or_b32_e32 v21, 7, v20
	s_mov_b64 s[28:29], -1
	s_mov_b64 s[74:75], -1
	s_and_saveexec_b64 s[44:45], vcc
	s_cbranch_execz .LBB0_724
	v_add_u32_e32 v22, v23, v4
	v_cmp_ge_u32_e32 vcc, v22, v19
	v_mov_b32_e32 v5, 0
	s_mov_b64 s[74:75], 0
	v_mov_b32_e32 v21, v20
	s_and_saveexec_b64 s[76:77], vcc
	s_mov_b64 s[74:75], exec
	v_or_b32_e32 v21, 6, v20
	v_mov_b32_e32 v5, v4
	v_mov_b32_e32 v22, v23
	s_or_b64 exec, exec, s[76:77]
	s_orn2_b64 s[74:75], s[74:75], exec
